# A mixer: far and dense full-stage paths loop on themselves with the step barrier right after the stage's last LDS read, next stage's K and bias tiles prefetched behind the last window
# speedup vs baseline: 1.0107x; 1.0052x over previous
; __device__ __forceinline__ float ex2(float x) { return __builtin_amdgcn_exp2f(x); }
; __device__ __forceinline__ f32x16 mfma32(bf16x8 a, bf16x8 b, f32x16 c) { return __builtin_amdgcn_mfma_f32_32x32x16_bf16(a, b, c, 0, 0, 0); }
; #define LOADK(kf_, cb_) do { _Pragma("unroll") for (int s_ = 0; s_ < 4; ++s_) kf_[s_] = *(const LAS bf16x8*)((cb_) + s_ * 1024); } while (0)
; #define LOADV(vf_, cb_) do { _Pragma("unroll") for (int d_ = 0; d_ < 2; ++d_) _Pragma("unroll") for (int s_ = 0; s_ < 2; ++s_) vf_[d_][s_] = *(const LAS bf16x8*)((cb_) + 4096 + (d_ * 2 + s_) * 1024); } while (0)
; #define LOADT(t_, tp_) do { const f32x4 a_ = *(const LAS f32x4*)(tp_), b_ = *(const LAS f32x4*)((tp_) + 16), c_ = *(const LAS f32x4*)((tp_) + 64), d_ = *(const LAS f32x4*)((tp_) + 80); \
;     t_ = (f32x16){a_[0], a_[1], a_[2], a_[3], b_[0], b_[1], b_[2], b_[3], c_[0], c_[1], c_[2], c_[3], d_[0], d_[1], d_[2], d_[3]}; } while (0)
; #define SCHED_FENCE() __builtin_amdgcn_sched_barrier(0)
; __device__ __forceinline__ void sm_A(f32x16& sc, float& l, bf16x8& p0, bf16x8& p1) {
; #pragma unroll
;     for (int i = 0; i < 16; ++i) { const float p = ex2(sc[i]); sc[i] = p; l += p; }
;     pack_p(sc, p0, p1);
; }
; __device__ __forceinline__ void pv4(const bf16x8 (&vf)[2][2], bf16x8 p0, bf16x8 p1, f32x16& o0, f32x16& o1) {
;     o0 = mfma32(vf[0][0], p0, o0); o1 = mfma32(vf[1][0], p0, o1); o0 = mfma32(vf[0][1], p1, o0); o1 = mfma32(vf[1][1], p1, o1);
; }
; __device__ __forceinline__ void sub_A(const bf16x8 (&kf)[4], const bf16x8 (&vf)[2][2], const bf16x8 (&qf)[4], f32x16 sc  , f32x16& o0, f32x16& o1, float& l) {
; #pragma unroll
;     for (int s = 0; s < 4; ++s) sc = mfma32(kf[s], qf[s], sc);
;     bf16x8 p0, p1; sm_A(sc, l, p0, p1);
;     pv4(vf, p0, p1, o0, o1);
; }
; __device__ __forceinline__ void blk_A(int b, int hd, int chunk  , const bf16_t* QK, const bf16_t* VT, bf16_t* mixed, LAS unsigned char* lds, const float* tblg, int tid, int lane, int wave) {
;     ...
;                 LOADK(kf, cb + u * 8192); LOADV(vf, cb + u * 8192);
;                 if (cA) { f32x16 tA; LOADT(tA, tb - (qbA - kb) * 128); SCHED_FENCE(); sub_A(kf, vf, qfA, tA, oA0, oA1, lA); }
;                 if (cB) { f32x16 tB; LOADT(tB, tb - (qbB - kb) * 128); SCHED_FENCE(); sub_A(kf, vf, qfB, tB, oB0, oB1, lB); }
.Lattn_a_far_top:
	s_waitcnt lgkmcnt(4)
	v_mfma_f32_32x32x16_bf16 v[80:95], v[144:147], v[96:99], v[80:95]
	v_mfma_f32_32x32x16_bf16 v[80:95], v[140:143], v[100:103], v[80:95]
	v_mfma_f32_32x32x16_bf16 v[80:95], v[136:139], v[112:115], v[80:95]
	v_mfma_f32_32x32x16_bf16 v[80:95], v[132:135], v[116:119], v[80:95]
	ds_read_b128 v[128:131], v0 offset:39168
	ds_read_b128 v[6:9], v0 offset:40192
	ds_read_b128 v[10:13], v0 offset:41216
	ds_read_b128 v[2:5], v0 offset:42240
	s_nop 5
	s_waitcnt lgkmcnt(4)
	v_mfma_f32_32x32x16_bf16 v[206:221], v[144:147], v[104:107], v[206:221]
	v_cndmask_b32_e64 v80, v80, v81, s[0:1]
	v_cndmask_b32_e64 v82, v82, v83, s[0:1]
	v_cndmask_b32_e64 v84, v84, v85, s[0:1]
	v_cndmask_b32_e64 v86, v86, v87, s[0:1]
	v_cndmask_b32_e64 v88, v88, v89, s[0:1]
	v_cndmask_b32_e64 v90, v90, v91, s[0:1]
	v_cndmask_b32_e64 v92, v92, v93, s[0:1]
	v_cndmask_b32_e64 v94, v94, v95, s[0:1]
	v_cndmask_b32_e64 v80, v80, v82, s[18:19]
	v_cndmask_b32_e64 v84, v84, v86, s[18:19]
	v_cndmask_b32_e64 v88, v88, v90, s[18:19]
	v_cndmask_b32_e64 v92, v92, v94, s[18:19]
	v_mfma_f32_32x32x16_bf16 v[206:221], v[140:143], v[108:111], v[206:221]
	v_cndmask_b32_e64 v80, v80, v84, s[56:57]
	v_cndmask_b32_e64 v88, v88, v92, s[56:57]
	v_exp_f32_e32 v80, v80
	v_exp_f32_e32 v88, v88
	s_mov_b32 vcc_lo, 0x00ff00ff
	s_mov_b32 vcc_hi, 0xff00ff00
	s_nop 0
	v_cndmask_b32_e32 v80, 0, v80, vcc
	v_cndmask_b32_e32 v88, 0, v88, vcc
	v_add_f32_e32 v156, v156, v80
	v_add_f32_e32 v156, v156, v88
	v_cvt_pk_bf16_f32 v166, v80, 0
	v_mfma_f32_32x32x16_bf16 v[206:221], v[136:139], v[120:123], v[206:221]
	v_cvt_pk_bf16_f32 v167, v88, 0
	v_lshlrev_b32_e32 v166, v157, v166
	v_lshlrev_b32_e32 v167, v157, v167
	s_mov_b32 vcc_lo, 0x03030303
	s_mov_b32 vcc_hi, 0x03030303
	s_nop 0
	v_cndmask_b32_e32 v194, 0, v166, vcc
	v_cndmask_b32_e32 v198, 0, v167, vcc
	s_mov_b32 vcc_lo, 0x0c0c0c0c
	s_mov_b32 vcc_hi, 0x0c0c0c0c
	s_nop 0
	v_cndmask_b32_e32 v195, 0, v166, vcc
	v_mfma_f32_32x32x16_bf16 v[206:221], v[132:135], v[124:127], v[206:221]
	ds_read_b128 v[144:147], v0 offset:43264
	ds_read_b128 v[140:143], v0 offset:44288
	ds_read_b128 v[136:139], v0 offset:45312
	ds_read_b128 v[132:135], v0 offset:46336
	v_cndmask_b32_e32 v199, 0, v167, vcc
	s_mov_b32 vcc_lo, 0x30303030
	s_mov_b32 vcc_hi, 0x30303030
	s_nop 0
	v_cndmask_b32_e32 v196, 0, v166, vcc
	v_cndmask_b32_e32 v200, 0, v167, vcc
	s_mov_b32 vcc_lo, 0xc0c0c0c0
	s_mov_b32 vcc_hi, 0xc0c0c0c0
	s_nop 0
	v_cndmask_b32_e32 v197, 0, v166, vcc
	v_cndmask_b32_e32 v201, 0, v167, vcc
	ds_read_b128 v[80:83], v154 offset:1152
	ds_read_b128 v[84:87], v154 offset:1168
	ds_read_b128 v[88:91], v154 offset:1216
	ds_read_b128 v[92:95], v154 offset:1232
	s_waitcnt lgkmcnt(8)
	v_mfma_f32_32x32x16_bf16 v[64:79], v[128:131], v[194:197], v[64:79]
	v_cndmask_b32_e64 v206, v206, v207, s[0:1]
	v_cndmask_b32_e64 v208, v208, v209, s[0:1]
	v_cndmask_b32_e64 v210, v210, v211, s[0:1]
	v_cndmask_b32_e64 v212, v212, v213, s[0:1]
	v_cndmask_b32_e64 v214, v214, v215, s[0:1]
	v_cndmask_b32_e64 v216, v216, v217, s[0:1]
	v_mfma_f32_32x32x16_bf16 v[48:63], v[10:13], v[194:197], v[48:63]
	v_cndmask_b32_e64 v218, v218, v219, s[0:1]
	v_cndmask_b32_e64 v220, v220, v221, s[0:1]
	v_cndmask_b32_e64 v206, v206, v208, s[18:19]
	v_cndmask_b32_e64 v210, v210, v212, s[18:19]
	v_cndmask_b32_e64 v214, v214, v216, s[18:19]
	v_cndmask_b32_e64 v218, v218, v220, s[18:19]
	v_mfma_f32_32x32x16_bf16 v[64:79], v[6:9], v[198:201], v[64:79]
	v_cndmask_b32_e64 v206, v206, v210, s[56:57]
	v_cndmask_b32_e64 v214, v214, v218, s[56:57]
	v_exp_f32_e32 v206, v206
	v_exp_f32_e32 v214, v214
	s_mov_b32 vcc_lo, 0x00ff00ff
	s_mov_b32 vcc_hi, 0xff00ff00
	v_mfma_f32_32x32x16_bf16 v[48:63], v[2:5], v[198:201], v[48:63]
	s_waitcnt lgkmcnt(0)
	s_nop 0
	v_cndmask_b32_e32 v206, 0, v206, vcc
	v_cndmask_b32_e32 v214, 0, v214, vcc
	v_add_f32_e32 v155, v155, v206
	v_add_f32_e32 v155, v155, v214
	v_cvt_pk_bf16_f32 v166, v206, 0
	v_mfma_f32_32x32x16_bf16 v[80:95], v[144:147], v[96:99], v[80:95]
	v_cvt_pk_bf16_f32 v167, v214, 0
	v_lshlrev_b32_e32 v166, v157, v166
	v_lshlrev_b32_e32 v167, v157, v167
	s_mov_b32 vcc_lo, 0x03030303
	s_mov_b32 vcc_hi, 0x03030303
	s_nop 0
	v_mfma_f32_32x32x16_bf16 v[80:95], v[140:143], v[100:103], v[80:95]
	v_cndmask_b32_e32 v158, 0, v166, vcc
	v_cndmask_b32_e32 v162, 0, v167, vcc
	s_mov_b32 vcc_lo, 0x0c0c0c0c
	s_mov_b32 vcc_hi, 0x0c0c0c0c
	s_nop 0
	v_cndmask_b32_e32 v159, 0, v166, vcc
	v_mfma_f32_32x32x16_bf16 v[80:95], v[136:139], v[112:115], v[80:95]
	v_cndmask_b32_e32 v163, 0, v167, vcc
	s_mov_b32 vcc_lo, 0x30303030
	s_mov_b32 vcc_hi, 0x30303030
	s_nop 0
	v_cndmask_b32_e32 v160, 0, v166, vcc
	v_cndmask_b32_e32 v164, 0, v167, vcc
	v_mfma_f32_32x32x16_bf16 v[80:95], v[132:135], v[116:119], v[80:95]
	s_mov_b32 vcc_lo, 0xc0c0c0c0
	s_mov_b32 vcc_hi, 0xc0c0c0c0
	s_nop 0
	v_cndmask_b32_e32 v161, 0, v166, vcc
	v_cndmask_b32_e32 v165, 0, v167, vcc
	s_nop 7
	ds_read_b128 v[206:209], v154 offset:128
	ds_read_b128 v[210:213], v154 offset:144
	ds_read_b128 v[214:217], v154 offset:192
	ds_read_b128 v[218:221], v154 offset:208
	v_mfma_f32_32x32x16_bf16 v[32:47], v[128:131], v[158:161], v[32:47]
	v_cndmask_b32_e64 v80, v80, v81, s[0:1]
	v_cndmask_b32_e64 v82, v82, v83, s[0:1]
	v_cndmask_b32_e64 v84, v84, v85, s[0:1]
	v_cndmask_b32_e64 v86, v86, v87, s[0:1]
	v_cndmask_b32_e64 v88, v88, v89, s[0:1]
	v_cndmask_b32_e64 v90, v90, v91, s[0:1]
	v_mfma_f32_32x32x16_bf16 v[16:31], v[10:13], v[158:161], v[16:31]
	v_cndmask_b32_e64 v92, v92, v93, s[0:1]
	v_cndmask_b32_e64 v94, v94, v95, s[0:1]
	v_cndmask_b32_e64 v80, v80, v82, s[18:19]
	v_cndmask_b32_e64 v84, v84, v86, s[18:19]
	v_cndmask_b32_e64 v88, v88, v90, s[18:19]
	v_cndmask_b32_e64 v92, v92, v94, s[18:19]
	v_mfma_f32_32x32x16_bf16 v[32:47], v[6:9], v[162:165], v[32:47]
	v_cndmask_b32_e64 v80, v80, v84, s[56:57]
	v_cndmask_b32_e64 v88, v88, v92, s[56:57]
	v_exp_f32_e32 v80, v80
	v_exp_f32_e32 v88, v88
	s_mov_b32 vcc_lo, 0x00ff00ff
	s_mov_b32 vcc_hi, 0xff00ff00
	v_mfma_f32_32x32x16_bf16 v[16:31], v[2:5], v[162:165], v[16:31]
	ds_read_b128 v[128:131], v0 offset:47360
	ds_read_b128 v[6:9], v0 offset:48384
	ds_read_b128 v[10:13], v0 offset:49408
	ds_read_b128 v[2:5], v0 offset:50432
	s_waitcnt lgkmcnt(4)
; #define LAS __attribute__((address_space(3)))
; __device__ __forceinline__ float ex2(float x) { return __builtin_amdgcn_exp2f(x); }
; __device__ __forceinline__ f32x16 mfma32(bf16x8 a, bf16x8 b, f32x16 c) { return __builtin_amdgcn_mfma_f32_32x32x16_bf16(a, b, c, 0, 0, 0); }
; #define WAITBAR2() asm volatile("s_waitcnt vmcnt(2) lgkmcnt(0)\n\ts_barrier" ::: "memory")
; #define LOADK(kf_, cb_) do { _Pragma("unroll") for (int s_ = 0; s_ < 4; ++s_) kf_[s_] = *(const LAS bf16x8*)((cb_) + s_ * 1024); } while (0)
; #define SCHED_FENCE() __builtin_amdgcn_sched_barrier(0)
; __device__ __forceinline__ void sm_A(f32x16& sc, float& l, bf16x8& p0, bf16x8& p1) {
; #pragma unroll
;     for (int i = 0; i < 16; ++i) { const float p = ex2(sc[i]); sc[i] = p; l += p; }
;     pack_p(sc, p0, p1);
; }
; __device__ __forceinline__ void pv4(const bf16x8 (&vf)[2][2], bf16x8 p0, bf16x8 p1, f32x16& o0, f32x16& o1) {
;     o0 = mfma32(vf[0][0], p0, o0); o1 = mfma32(vf[1][0], p0, o1); o0 = mfma32(vf[0][1], p1, o0); o1 = mfma32(vf[1][1], p1, o1);
; }
; __device__ __forceinline__ void sub_A(const bf16x8 (&kf)[4], const bf16x8 (&vf)[2][2], const bf16x8 (&qf)[4], f32x16 sc  , f32x16& o0, f32x16& o1, float& l) {
; #pragma unroll
;     for (int s = 0; s < 4; ++s) sc = mfma32(kf[s], qf[s], sc);
;     bf16x8 p0, p1; sm_A(sc, l, p0, p1);
;     pv4(vf, p0, p1, o0, o1);
; }
; __device__ __forceinline__ void blk_A(int b, int hd, int chunk  , const bf16_t* QK, const bf16_t* VT, bf16_t* mixed, LAS unsigned char* lds, const float* tblg, int tid, int lane, int wave) {
;     ...
;     for (int sbk = sb_lo; sbk <= sb_end; ++sbk) {
;         ISSUE_UP();
;         const LAS unsigned char* cb = sb + slot_c * STG_BYTES + lane * 16;
; #pragma unroll
;         for (int u = 0; u < 2; ++u) {
;             const int kb = 2 * sbk + u; const bool cA = kb <= qbA && kb + 64 >= qbA, cB = kb <= qbB && kb + 64 >= qbB;
;             if (cA || cB) {
;                 bf16x8 kf[4], vf[2][2];
;                 LOADK(kf, cb + u * 8192); LOADV(vf, cb + u * 8192);
;                 if (cA) { f32x16 tA; LOADT(tA, tb - (qbA - kb) * 128); SCHED_FENCE(); sub_A(kf, vf, qfA, tA, oA0, oA1, lA); }
;                 if (cB) { f32x16 tB; LOADT(tB, tb - (qbB - kb) * 128); SCHED_FENCE(); sub_A(kf, vf, qfB, tB, oB0, oB1, lB); }
;             }
;         }
;         WAITBAR2();
;         slot_c = slot_c == NSTG - 1 ? 0 : slot_c + 1;
;     }
	s_nop 0
	v_cndmask_b32_e32 v80, 0, v80, vcc
	v_cndmask_b32_e32 v88, 0, v88, vcc
	v_add_f32_e32 v156, v156, v80
	v_add_f32_e32 v156, v156, v88
	v_cvt_pk_bf16_f32 v166, v80, 0
	v_mfma_f32_32x32x16_bf16 v[206:221], v[144:147], v[104:107], v[206:221]
	v_cvt_pk_bf16_f32 v167, v88, 0
	v_lshlrev_b32_e32 v166, v157, v166
	v_lshlrev_b32_e32 v167, v157, v167
	s_mov_b32 vcc_lo, 0x03030303
	s_mov_b32 vcc_hi, 0x03030303
	s_nop 0
	v_mfma_f32_32x32x16_bf16 v[206:221], v[140:143], v[108:111], v[206:221]
	v_cndmask_b32_e32 v194, 0, v166, vcc
	v_cndmask_b32_e32 v198, 0, v167, vcc
	s_mov_b32 vcc_lo, 0x0c0c0c0c
	s_mov_b32 vcc_hi, 0x0c0c0c0c
	s_nop 0
	v_cndmask_b32_e32 v195, 0, v166, vcc
	v_mfma_f32_32x32x16_bf16 v[206:221], v[136:139], v[120:123], v[206:221]
	v_cndmask_b32_e32 v199, 0, v167, vcc
	s_mov_b32 vcc_lo, 0x30303030
	s_mov_b32 vcc_hi, 0x30303030
	s_nop 0
	v_cndmask_b32_e32 v196, 0, v166, vcc
	v_cndmask_b32_e32 v200, 0, v167, vcc
	v_mfma_f32_32x32x16_bf16 v[206:221], v[132:135], v[124:127], v[206:221]
	s_mov_b32 vcc_lo, 0xc0c0c0c0
	s_mov_b32 vcc_hi, 0xc0c0c0c0
	s_nop 0
	v_cndmask_b32_e32 v197, 0, v166, vcc
	v_cndmask_b32_e32 v201, 0, v167, vcc
	s_nop 9
	s_waitcnt vmcnt(2) lgkmcnt(0)
	s_barrier
	s_add_i32 s0, s54, 1
	s_add_i32 s1, s35, 1
	s_cmp_lg_u32 s35, 2
	s_cselect_b32 s35, s1, 0
	s_add_i32 s1, s53, 1
	s_cmp_lg_u32 s53, 2
	s_cselect_b32 s53, s1, 0
	s_add_i32 s1, s54, -2
	s_add_i32 s52, s52, 2
	s_cmp_lt_i32 s1, s27
	v_add_u32_e32 v154, 0x100, v154
	s_cbranch_scc0 .Lattn_a_far_exit
	s_mov_b32 s54, s0
	s_min_i32 s0, s54, s27
	s_ashr_i32 s1, s0, 31
	s_lshl_b32 s55, s35, 14
	s_lshl_b64 s[18:19], s[0:1], 18
	v_lshl_add_u64 v[14:15], v[150:151], 0, s[18:19]
	s_add_i32 s18, s31, s55
	s_lshl_b32 s0, s0, 6
	v_lshl_add_u64 v[14:15], v[14:15], 0, s[12:13]
	s_add_i32 m0, s18, 0x8900
	s_ashr_i32 s1, s0, 31
	global_load_lds_dwordx4 v[14:15], off
	v_lshl_add_u64 v[14:15], s[0:1], 1, v[152:153]
	s_add_i32 m0, s18, 0x9900
	s_lshl_b32 s55, s53, 14
	global_load_lds_dwordx4 v[14:15], off
	s_add_i32 s1, s30, 0xffffffee
	s_cmp_le_i32 s52, s1
	s_cbranch_scc0 .Lattn_a_far_to_dense
	v_add_u32_e32 v0, s55, v179
	s_mov_b32 s0, 0xaaaaaaaa
	s_mov_b32 s1, 0xaaaaaaaa
	s_mov_b32 s18, 0xcccccccc
	s_mov_b32 s19, 0xcccccccc
	ds_read_b128 v[144:147], v0 offset:35072
	ds_read_b128 v[140:143], v0 offset:36096
	ds_read_b128 v[136:139], v0 offset:37120
	ds_read_b128 v[132:135], v0 offset:38144
	ds_read_b128 v[80:83], v154 offset:1024
	ds_read_b128 v[84:87], v154 offset:1040
	ds_read_b128 v[88:91], v154 offset:1088
	ds_read_b128 v[92:95], v154 offset:1104
	v_mfma_f32_32x32x16_bf16 v[64:79], v[128:131], v[194:197], v[64:79]
	v_cndmask_b32_e64 v206, v206, v207, s[0:1]
	v_cndmask_b32_e64 v208, v208, v209, s[0:1]
	v_cndmask_b32_e64 v210, v210, v211, s[0:1]
	v_cndmask_b32_e64 v212, v212, v213, s[0:1]
	v_cndmask_b32_e64 v214, v214, v215, s[0:1]
	v_cndmask_b32_e64 v216, v216, v217, s[0:1]
	v_cndmask_b32_e64 v218, v218, v219, s[0:1]
	v_cndmask_b32_e64 v220, v220, v221, s[0:1]
	v_cndmask_b32_e64 v206, v206, v208, s[18:19]
	v_cndmask_b32_e64 v210, v210, v212, s[18:19]
	v_cndmask_b32_e64 v214, v214, v216, s[18:19]
	v_cndmask_b32_e64 v218, v218, v220, s[18:19]
	v_mfma_f32_32x32x16_bf16 v[48:63], v[10:13], v[194:197], v[48:63]
	v_cndmask_b32_e64 v206, v206, v210, s[56:57]
	v_cndmask_b32_e64 v214, v214, v218, s[56:57]
	v_exp_f32_e32 v206, v206
	v_exp_f32_e32 v214, v214
	s_mov_b32 vcc_lo, 0x00ff00ff
	s_mov_b32 vcc_hi, 0xff00ff00
	s_nop 0
	v_cndmask_b32_e32 v206, 0, v206, vcc
	v_cndmask_b32_e32 v214, 0, v214, vcc
	v_add_f32_e32 v155, v155, v206
	v_add_f32_e32 v155, v155, v214
	v_cvt_pk_bf16_f32 v166, v206, 0
	v_mfma_f32_32x32x16_bf16 v[64:79], v[6:9], v[198:201], v[64:79]
	v_cvt_pk_bf16_f32 v167, v214, 0
	v_lshlrev_b32_e32 v166, v157, v166
	v_lshlrev_b32_e32 v167, v157, v167
	s_mov_b32 vcc_lo, 0x03030303
	s_mov_b32 vcc_hi, 0x03030303
	s_nop 0
	v_cndmask_b32_e32 v158, 0, v166, vcc
	v_cndmask_b32_e32 v162, 0, v167, vcc
	s_mov_b32 vcc_lo, 0x0c0c0c0c
	s_mov_b32 vcc_hi, 0x0c0c0c0c
	s_nop 0
	v_cndmask_b32_e32 v159, 0, v166, vcc
	v_mfma_f32_32x32x16_bf16 v[48:63], v[2:5], v[198:201], v[48:63]
	v_cndmask_b32_e32 v163, 0, v167, vcc
	s_mov_b32 vcc_lo, 0x30303030
	s_mov_b32 vcc_hi, 0x30303030
	s_nop 0
	v_cndmask_b32_e32 v160, 0, v166, vcc
	v_cndmask_b32_e32 v164, 0, v167, vcc
	s_mov_b32 vcc_lo, 0xc0c0c0c0
	s_mov_b32 vcc_hi, 0xc0c0c0c0
	s_nop 0
	v_cndmask_b32_e32 v161, 0, v166, vcc
	v_cndmask_b32_e32 v165, 0, v167, vcc
	ds_read_b128 v[206:209], v154 offset:0
	ds_read_b128 v[210:213], v154 offset:16
	ds_read_b128 v[214:217], v154 offset:64
	ds_read_b128 v[218:221], v154 offset:80
	s_nop 1
	v_mfma_f32_32x32x16_bf16 v[32:47], v[128:131], v[158:161], v[32:47]
	v_mfma_f32_32x32x16_bf16 v[16:31], v[10:13], v[158:161], v[16:31]
	v_mfma_f32_32x32x16_bf16 v[32:47], v[6:9], v[162:165], v[32:47]
	v_mfma_f32_32x32x16_bf16 v[16:31], v[2:5], v[162:165], v[16:31]
	s_branch .Lattn_a_far_top
; #define LAS __attribute__((address_space(3)))
; __device__ __forceinline__ float ex2(float x) { return __builtin_amdgcn_exp2f(x); }
; __device__ __forceinline__ f32x16 mfma32(bf16x8 a, bf16x8 b, f32x16 c) { return __builtin_amdgcn_mfma_f32_32x32x16_bf16(a, b, c, 0, 0, 0); }
; #define WAITBAR2() asm volatile("s_waitcnt vmcnt(2) lgkmcnt(0)\n\ts_barrier" ::: "memory")
; #define DRAIN_DMA() asm volatile("s_waitcnt vmcnt(0)" ::: "memory")
; #define SCHED_FENCE() __builtin_amdgcn_sched_barrier(0)
; __device__ __forceinline__ void sm_A(f32x16& sc, float& l, bf16x8& p0, bf16x8& p1) {
; #pragma unroll
;     for (int i = 0; i < 16; ++i) { const float p = ex2(sc[i]); sc[i] = p; l += p; }
;     pack_p(sc, p0, p1);
; }
; __device__ __forceinline__ void pv4(const bf16x8 (&vf)[2][2], bf16x8 p0, bf16x8 p1, f32x16& o0, f32x16& o1) {
;     o0 = mfma32(vf[0][0], p0, o0); o1 = mfma32(vf[1][0], p0, o1); o0 = mfma32(vf[0][1], p1, o0); o1 = mfma32(vf[1][1], p1, o1);
; }
; __device__ __forceinline__ void sub_A(const bf16x8 (&kf)[4], const bf16x8 (&vf)[2][2], const bf16x8 (&qf)[4], f32x16 sc  , f32x16& o0, f32x16& o1, float& l) {
; #pragma unroll
;     for (int s = 0; s < 4; ++s) sc = mfma32(kf[s], qf[s], sc);
;     bf16x8 p0, p1; sm_A(sc, l, p0, p1);
;     pv4(vf, p0, p1, o0, o1);
; }
; __device__ __forceinline__ void blk_A(int b, int hd, int chunk  , const bf16_t* QK, const bf16_t* VT, bf16_t* mixed, LAS unsigned char* lds, const float* tblg, int tid, int lane, int wave) {
;     ...
;     for (int sbk = sb_lo; sbk <= sb_end; ++sbk) {
;         ISSUE_UP();
;         const LAS unsigned char* cb = sb + slot_c * STG_BYTES + lane * 16;
; #pragma unroll
;         for (int u = 0; u < 2; ++u) {
;             const int kb = 2 * sbk + u; const bool cA = kb <= qbA && kb + 64 >= qbA, cB = kb <= qbB && kb + 64 >= qbB;
;             if (cA || cB) {
;                 bf16x8 kf[4], vf[2][2];
;                 LOADK(kf, cb + u * 8192); LOADV(vf, cb + u * 8192);
;                 if (cA) { f32x16 tA; LOADT(tA, tb - (qbA - kb) * 128); SCHED_FENCE(); sub_A(kf, vf, qfA, tA, oA0, oA1, lA); }
;                 if (cB) { f32x16 tB; LOADT(tB, tb - (qbB - kb) * 128); SCHED_FENCE(); sub_A(kf, vf, qfB, tB, oB0, oB1, lB); }
;             }
;         }
;         WAITBAR2();
;         slot_c = slot_c == NSTG - 1 ? 0 : slot_c + 1;
;     }
;     DRAIN_DMA();
.Lattn_a_far_to_dense:
	s_mov_b32 s0, 0xaaaaaaaa
	s_mov_b32 s1, 0xaaaaaaaa
	s_mov_b32 s18, 0xcccccccc
	s_mov_b32 s19, 0xcccccccc
	v_mfma_f32_32x32x16_bf16 v[64:79], v[128:131], v[194:197], v[64:79]
	v_cndmask_b32_e64 v206, v206, v207, s[0:1]
	v_cndmask_b32_e64 v208, v208, v209, s[0:1]
	v_cndmask_b32_e64 v210, v210, v211, s[0:1]
	v_cndmask_b32_e64 v212, v212, v213, s[0:1]
	v_cndmask_b32_e64 v214, v214, v215, s[0:1]
	v_cndmask_b32_e64 v216, v216, v217, s[0:1]
	v_cndmask_b32_e64 v218, v218, v219, s[0:1]
	v_cndmask_b32_e64 v220, v220, v221, s[0:1]
	v_cndmask_b32_e64 v206, v206, v208, s[18:19]
	v_cndmask_b32_e64 v210, v210, v212, s[18:19]
	v_cndmask_b32_e64 v214, v214, v216, s[18:19]
	v_cndmask_b32_e64 v218, v218, v220, s[18:19]
	v_mfma_f32_32x32x16_bf16 v[48:63], v[10:13], v[194:197], v[48:63]
	v_cndmask_b32_e64 v206, v206, v210, s[56:57]
	v_cndmask_b32_e64 v214, v214, v218, s[56:57]
	v_exp_f32_e32 v206, v206
	v_exp_f32_e32 v214, v214
	s_mov_b32 vcc_lo, 0x00ff00ff
	s_mov_b32 vcc_hi, 0xff00ff00
	s_nop 0
	v_cndmask_b32_e32 v206, 0, v206, vcc
	v_cndmask_b32_e32 v214, 0, v214, vcc
	v_add_f32_e32 v155, v155, v206
	v_add_f32_e32 v155, v155, v214
	v_cvt_pk_bf16_f32 v166, v206, 0
	v_mfma_f32_32x32x16_bf16 v[64:79], v[6:9], v[198:201], v[64:79]
	v_cvt_pk_bf16_f32 v167, v214, 0
	v_lshlrev_b32_e32 v166, v157, v166
	v_lshlrev_b32_e32 v167, v157, v167
	s_mov_b32 vcc_lo, 0x03030303
	s_mov_b32 vcc_hi, 0x03030303
	s_nop 0
	v_cndmask_b32_e32 v158, 0, v166, vcc
	v_cndmask_b32_e32 v162, 0, v167, vcc
	s_mov_b32 vcc_lo, 0x0c0c0c0c
	s_mov_b32 vcc_hi, 0x0c0c0c0c
	s_nop 0
	v_cndmask_b32_e32 v159, 0, v166, vcc
	v_mfma_f32_32x32x16_bf16 v[48:63], v[2:5], v[198:201], v[48:63]
	v_cndmask_b32_e32 v163, 0, v167, vcc
	s_mov_b32 vcc_lo, 0x30303030
	s_mov_b32 vcc_hi, 0x30303030
	s_nop 0
	v_cndmask_b32_e32 v160, 0, v166, vcc
	v_cndmask_b32_e32 v164, 0, v167, vcc
	s_mov_b32 vcc_lo, 0xc0c0c0c0
	s_mov_b32 vcc_hi, 0xc0c0c0c0
	s_nop 0
	v_cndmask_b32_e32 v161, 0, v166, vcc
	v_cndmask_b32_e32 v165, 0, v167, vcc
	s_nop 1
	v_mfma_f32_32x32x16_bf16 v[32:47], v[128:131], v[158:161], v[32:47]
	v_mfma_f32_32x32x16_bf16 v[16:31], v[10:13], v[158:161], v[16:31]
	v_mfma_f32_32x32x16_bf16 v[32:47], v[6:9], v[162:165], v[32:47]
	v_mfma_f32_32x32x16_bf16 v[16:31], v[2:5], v[162:165], v[16:31]
	v_add_u32_e32 v0, s55, v179
	s_branch .Lattn_a_dense
.Lattn_a_far_exit:
	s_mov_b32 s0, 0xaaaaaaaa
	s_mov_b32 s1, 0xaaaaaaaa
	v_mfma_f32_32x32x16_bf16 v[64:79], v[128:131], v[194:197], v[64:79]
	v_cndmask_b32_e64 v206, v206, v207, s[0:1]
	v_cndmask_b32_e64 v208, v208, v209, s[0:1]
	v_cndmask_b32_e64 v210, v210, v211, s[0:1]
	v_cndmask_b32_e64 v212, v212, v213, s[0:1]
	v_cndmask_b32_e64 v214, v214, v215, s[0:1]
	v_cndmask_b32_e64 v216, v216, v217, s[0:1]
	v_cndmask_b32_e64 v218, v218, v219, s[0:1]
	v_cndmask_b32_e64 v220, v220, v221, s[0:1]
	v_cndmask_b32_e64 v206, v206, v208, s[18:19]
	v_cndmask_b32_e64 v210, v210, v212, s[18:19]
	v_cndmask_b32_e64 v214, v214, v216, s[18:19]
	v_cndmask_b32_e64 v218, v218, v220, s[18:19]
	v_mfma_f32_32x32x16_bf16 v[48:63], v[10:13], v[194:197], v[48:63]
	v_cndmask_b32_e64 v206, v206, v210, s[56:57]
	v_cndmask_b32_e64 v214, v214, v218, s[56:57]
	v_exp_f32_e32 v206, v206
	v_exp_f32_e32 v214, v214
	s_mov_b32 vcc_lo, 0x00ff00ff
	s_mov_b32 vcc_hi, 0xff00ff00
	s_nop 0
	v_cndmask_b32_e32 v206, 0, v206, vcc
	v_cndmask_b32_e32 v214, 0, v214, vcc
	v_add_f32_e32 v155, v155, v206
	v_add_f32_e32 v155, v155, v214
	v_cvt_pk_bf16_f32 v166, v206, 0
	v_mfma_f32_32x32x16_bf16 v[64:79], v[6:9], v[198:201], v[64:79]
	v_cvt_pk_bf16_f32 v167, v214, 0
	v_lshlrev_b32_e32 v166, v157, v166
	v_lshlrev_b32_e32 v167, v157, v167
	s_mov_b32 vcc_lo, 0x03030303
	s_mov_b32 vcc_hi, 0x03030303
	s_nop 0
	v_cndmask_b32_e32 v158, 0, v166, vcc
	v_cndmask_b32_e32 v162, 0, v167, vcc
	s_mov_b32 vcc_lo, 0x0c0c0c0c
	s_mov_b32 vcc_hi, 0x0c0c0c0c
	s_nop 0
	v_cndmask_b32_e32 v159, 0, v166, vcc
	v_mfma_f32_32x32x16_bf16 v[48:63], v[2:5], v[198:201], v[48:63]
	v_cndmask_b32_e32 v163, 0, v167, vcc
	s_mov_b32 vcc_lo, 0x30303030
	s_mov_b32 vcc_hi, 0x30303030
	s_nop 0
	v_cndmask_b32_e32 v160, 0, v166, vcc
	v_cndmask_b32_e32 v164, 0, v167, vcc
	s_mov_b32 vcc_lo, 0xc0c0c0c0
	s_mov_b32 vcc_hi, 0xc0c0c0c0
	s_nop 0
	v_cndmask_b32_e32 v161, 0, v166, vcc
	v_cndmask_b32_e32 v165, 0, v167, vcc
	s_nop 1
	v_mfma_f32_32x32x16_bf16 v[32:47], v[128:131], v[158:161], v[32:47]
	v_mfma_f32_32x32x16_bf16 v[16:31], v[10:13], v[158:161], v[16:31]
	v_mfma_f32_32x32x16_bf16 v[32:47], v[6:9], v[162:165], v[32:47]
	v_mfma_f32_32x32x16_bf16 v[16:31], v[2:5], v[162:165], v[16:31]
	s_branch .LBB0_420

; __device__ __forceinline__ float ex2(float x) { return __builtin_amdgcn_exp2f(x); }
; __device__ __forceinline__ f32x16 mfma32(bf16x8 a, bf16x8 b, f32x16 c) { return __builtin_amdgcn_mfma_f32_32x32x16_bf16(a, b, c, 0, 0, 0); }
; __device__ __forceinline__ void sm_A(f32x16& sc, float& l, bf16x8& p0, bf16x8& p1) {
; #pragma unroll
;     for (int i = 0; i < 16; ++i) { const float p = ex2(sc[i]); sc[i] = p; l += p; }
;     pack_p(sc, p0, p1);
; }
; __device__ __forceinline__ void pv4(const bf16x8 (&vf)[2][2], bf16x8 p0, bf16x8 p1, f32x16& o0, f32x16& o1) {
;     o0 = mfma32(vf[0][0], p0, o0); o1 = mfma32(vf[1][0], p0, o1); o0 = mfma32(vf[0][1], p1, o0); o1 = mfma32(vf[1][1], p1, o1);
; }
; __device__ __forceinline__ void sub_A(const bf16x8 (&kf)[4], const bf16x8 (&vf)[2][2], const bf16x8 (&qf)[4], f32x16 sc  , f32x16& o0, f32x16& o1, float& l) {
; #pragma unroll
;     for (int s = 0; s < 4; ++s) sc = mfma32(kf[s], qf[s], sc);
;     bf16x8 p0, p1; sm_A(sc, l, p0, p1);
;     pv4(vf, p0, p1, o0, o1);
; }
.Lattn_a_dense_top:
	s_waitcnt lgkmcnt(4)
	v_mfma_f32_32x32x16_bf16 v[80:95], v[144:147], v[96:99], v[80:95]
	v_mfma_f32_32x32x16_bf16 v[80:95], v[140:143], v[100:103], v[80:95]
	v_mfma_f32_32x32x16_bf16 v[80:95], v[136:139], v[112:115], v[80:95]
	v_mfma_f32_32x32x16_bf16 v[80:95], v[132:135], v[116:119], v[80:95]
	ds_read_b128 v[128:131], v0 offset:39168
	ds_read_b128 v[6:9], v0 offset:40192
	ds_read_b128 v[10:13], v0 offset:41216
	ds_read_b128 v[2:5], v0 offset:42240
	s_nop 5
	s_waitcnt lgkmcnt(4)
	v_mfma_f32_32x32x16_bf16 v[206:221], v[144:147], v[104:107], v[206:221]
	v_exp_f32_e32 v80, v80
	v_exp_f32_e32 v81, v81
	v_exp_f32_e32 v82, v82
	v_exp_f32_e32 v83, v83
	v_add_f32_e32 v156, v80, v156
	v_add_f32_e32 v156, v81, v156
	v_add_f32_e32 v156, v82, v156
	v_add_f32_e32 v156, v83, v156
	v_cvt_pk_bf16_f32 v194, v80, v81
	v_cvt_pk_bf16_f32 v195, v82, v83
	v_mfma_f32_32x32x16_bf16 v[206:221], v[140:143], v[108:111], v[206:221]
	v_exp_f32_e32 v84, v84
	v_exp_f32_e32 v85, v85
	v_exp_f32_e32 v86, v86
	v_exp_f32_e32 v87, v87
	v_add_f32_e32 v156, v84, v156
	v_add_f32_e32 v156, v85, v156
	v_add_f32_e32 v156, v86, v156
	v_add_f32_e32 v156, v87, v156
	v_cvt_pk_bf16_f32 v196, v84, v85
	v_cvt_pk_bf16_f32 v197, v86, v87
	v_mfma_f32_32x32x16_bf16 v[206:221], v[136:139], v[120:123], v[206:221]
	v_exp_f32_e32 v88, v88
	v_exp_f32_e32 v89, v89
	v_exp_f32_e32 v90, v90
	v_exp_f32_e32 v91, v91
	v_add_f32_e32 v156, v88, v156
	v_add_f32_e32 v156, v89, v156
	v_add_f32_e32 v156, v90, v156
	v_add_f32_e32 v156, v91, v156
	v_cvt_pk_bf16_f32 v198, v88, v89
	v_cvt_pk_bf16_f32 v199, v90, v91
	v_mfma_f32_32x32x16_bf16 v[206:221], v[132:135], v[124:127], v[206:221]
	ds_read_b128 v[144:147], v0 offset:43264
	ds_read_b128 v[140:143], v0 offset:44288
	ds_read_b128 v[136:139], v0 offset:45312
	ds_read_b128 v[132:135], v0 offset:46336
	v_exp_f32_e32 v92, v92
	v_exp_f32_e32 v93, v93
	v_exp_f32_e32 v94, v94
	v_exp_f32_e32 v95, v95
	v_add_f32_e32 v156, v92, v156
	v_add_f32_e32 v156, v93, v156
	v_add_f32_e32 v156, v94, v156
	v_add_f32_e32 v156, v95, v156
	v_cvt_pk_bf16_f32 v200, v92, v93
	v_cvt_pk_bf16_f32 v201, v94, v95
	ds_read_b128 v[80:83], v154 offset:1152
	ds_read_b128 v[84:87], v154 offset:1168
	ds_read_b128 v[88:91], v154 offset:1216
	ds_read_b128 v[92:95], v154 offset:1232
	s_waitcnt lgkmcnt(8)
	v_mfma_f32_32x32x16_bf16 v[64:79], v[128:131], v[194:197], v[64:79]
	v_exp_f32_e32 v206, v206
	v_exp_f32_e32 v207, v207
	v_exp_f32_e32 v208, v208
	v_exp_f32_e32 v209, v209
	v_mfma_f32_32x32x16_bf16 v[48:63], v[10:13], v[194:197], v[48:63]
	v_add_f32_e32 v155, v206, v155
	v_add_f32_e32 v155, v207, v155
	v_add_f32_e32 v155, v208, v155
	v_add_f32_e32 v155, v209, v155
	v_cvt_pk_bf16_f32 v158, v206, v207
	v_cvt_pk_bf16_f32 v159, v208, v209
	v_mfma_f32_32x32x16_bf16 v[64:79], v[6:9], v[198:201], v[64:79]
	v_exp_f32_e32 v210, v210
	v_exp_f32_e32 v211, v211
	v_exp_f32_e32 v212, v212
	v_exp_f32_e32 v213, v213
	v_mfma_f32_32x32x16_bf16 v[48:63], v[2:5], v[198:201], v[48:63]
	s_waitcnt lgkmcnt(0)
	v_add_f32_e32 v155, v210, v155
	v_add_f32_e32 v155, v211, v155
	v_add_f32_e32 v155, v212, v155
	v_add_f32_e32 v155, v213, v155
	v_cvt_pk_bf16_f32 v160, v210, v211
	v_cvt_pk_bf16_f32 v161, v212, v213
	v_mfma_f32_32x32x16_bf16 v[80:95], v[144:147], v[96:99], v[80:95]
	v_exp_f32_e32 v214, v214
	v_exp_f32_e32 v215, v215
	v_exp_f32_e32 v216, v216
	v_exp_f32_e32 v217, v217
	v_mfma_f32_32x32x16_bf16 v[80:95], v[140:143], v[100:103], v[80:95]
	v_add_f32_e32 v155, v214, v155
	v_add_f32_e32 v155, v215, v155
	v_add_f32_e32 v155, v216, v155
	v_add_f32_e32 v155, v217, v155
	v_cvt_pk_bf16_f32 v162, v214, v215
	v_cvt_pk_bf16_f32 v163, v216, v217
	v_mfma_f32_32x32x16_bf16 v[80:95], v[136:139], v[112:115], v[80:95]
	v_exp_f32_e32 v218, v218
	v_exp_f32_e32 v219, v219
	v_exp_f32_e32 v220, v220
	v_exp_f32_e32 v221, v221
	v_mfma_f32_32x32x16_bf16 v[80:95], v[132:135], v[116:119], v[80:95]
	v_add_f32_e32 v155, v218, v155
	v_add_f32_e32 v155, v219, v155
	v_add_f32_e32 v155, v220, v155
	v_add_f32_e32 v155, v221, v155
	v_cvt_pk_bf16_f32 v164, v218, v219
	v_cvt_pk_bf16_f32 v165, v220, v221
	ds_read_b128 v[206:209], v154 offset:128
	ds_read_b128 v[210:213], v154 offset:144
	ds_read_b128 v[214:217], v154 offset:192
	ds_read_b128 v[218:221], v154 offset:208
	s_nop 3
	v_mfma_f32_32x32x16_bf16 v[32:47], v[128:131], v[158:161], v[32:47]
	v_exp_f32_e32 v80, v80
	v_exp_f32_e32 v81, v81
	v_exp_f32_e32 v82, v82
	v_exp_f32_e32 v83, v83
	v_mfma_f32_32x32x16_bf16 v[16:31], v[10:13], v[158:161], v[16:31]
	v_add_f32_e32 v156, v80, v156
	v_add_f32_e32 v156, v81, v156
	v_add_f32_e32 v156, v82, v156
	v_add_f32_e32 v156, v83, v156
	v_cvt_pk_bf16_f32 v194, v80, v81
	v_cvt_pk_bf16_f32 v195, v82, v83
	v_mfma_f32_32x32x16_bf16 v[32:47], v[6:9], v[162:165], v[32:47]
	v_exp_f32_e32 v84, v84
	v_exp_f32_e32 v85, v85
	v_exp_f32_e32 v86, v86
	v_exp_f32_e32 v87, v87
	v_mfma_f32_32x32x16_bf16 v[16:31], v[2:5], v[162:165], v[16:31]
	ds_read_b128 v[128:131], v0 offset:47360
	ds_read_b128 v[6:9], v0 offset:48384
	ds_read_b128 v[10:13], v0 offset:49408
	ds_read_b128 v[2:5], v0 offset:50432
	s_waitcnt lgkmcnt(4)
	v_add_f32_e32 v156, v84, v156
	v_add_f32_e32 v156, v85, v156
	v_add_f32_e32 v156, v86, v156
	v_add_f32_e32 v156, v87, v156
	v_cvt_pk_bf16_f32 v196, v84, v85
	v_cvt_pk_bf16_f32 v197, v86, v87
	v_mfma_f32_32x32x16_bf16 v[206:221], v[144:147], v[104:107], v[206:221]
	v_exp_f32_e32 v88, v88
	v_exp_f32_e32 v89, v89
	v_exp_f32_e32 v90, v90
	v_exp_f32_e32 v91, v91
	v_mfma_f32_32x32x16_bf16 v[206:221], v[140:143], v[108:111], v[206:221]
	v_add_f32_e32 v156, v88, v156
	v_add_f32_e32 v156, v89, v156
	v_add_f32_e32 v156, v90, v156
	v_add_f32_e32 v156, v91, v156
	v_cvt_pk_bf16_f32 v198, v88, v89
	v_cvt_pk_bf16_f32 v199, v90, v91
	v_mfma_f32_32x32x16_bf16 v[206:221], v[136:139], v[120:123], v[206:221]
	v_exp_f32_e32 v92, v92
	v_exp_f32_e32 v93, v93
	v_exp_f32_e32 v94, v94
	v_exp_f32_e32 v95, v95
	v_mfma_f32_32x32x16_bf16 v[206:221], v[132:135], v[124:127], v[206:221]
	v_add_f32_e32 v156, v92, v156
	v_add_f32_e32 v156, v93, v156
	v_add_f32_e32 v156, v94, v156
	v_add_f32_e32 v156, v95, v156
	v_cvt_pk_bf16_f32 v200, v92, v93
	v_cvt_pk_bf16_f32 v201, v94, v95
	s_waitcnt vmcnt(2) lgkmcnt(0)
	s_barrier
; #define LAS __attribute__((address_space(3)))
; __device__ __forceinline__ float ex2(float x) { return __builtin_amdgcn_exp2f(x); }
; __device__ __forceinline__ f32x16 mfma32(bf16x8 a, bf16x8 b, f32x16 c) { return __builtin_amdgcn_mfma_f32_32x32x16_bf16(a, b, c, 0, 0, 0); }
; #define WAITBAR2() asm volatile("s_waitcnt vmcnt(2) lgkmcnt(0)\n\ts_barrier" ::: "memory")
; #define LOADK(kf_, cb_) do { _Pragma("unroll") for (int s_ = 0; s_ < 4; ++s_) kf_[s_] = *(const LAS bf16x8*)((cb_) + s_ * 1024); } while (0)
; #define SCHED_FENCE() __builtin_amdgcn_sched_barrier(0)
; __device__ __forceinline__ void sm_A(f32x16& sc, float& l, bf16x8& p0, bf16x8& p1) {
; #pragma unroll
;     for (int i = 0; i < 16; ++i) { const float p = ex2(sc[i]); sc[i] = p; l += p; }
;     pack_p(sc, p0, p1);
; }
; __device__ __forceinline__ void pv4(const bf16x8 (&vf)[2][2], bf16x8 p0, bf16x8 p1, f32x16& o0, f32x16& o1) {
;     o0 = mfma32(vf[0][0], p0, o0); o1 = mfma32(vf[1][0], p0, o1); o0 = mfma32(vf[0][1], p1, o0); o1 = mfma32(vf[1][1], p1, o1);
; }
; __device__ __forceinline__ void sub_A(const bf16x8 (&kf)[4], const bf16x8 (&vf)[2][2], const bf16x8 (&qf)[4], f32x16 sc  , f32x16& o0, f32x16& o1, float& l) {
; #pragma unroll
;     for (int s = 0; s < 4; ++s) sc = mfma32(kf[s], qf[s], sc);
;     bf16x8 p0, p1; sm_A(sc, l, p0, p1);
;     pv4(vf, p0, p1, o0, o1);
; }
; __device__ __forceinline__ void blk_A(int b, int hd, int chunk  , const bf16_t* QK, const bf16_t* VT, bf16_t* mixed, LAS unsigned char* lds, const float* tblg, int tid, int lane, int wave) {
;     ...
;     for (int sbk = sb_lo; sbk <= sb_end; ++sbk) {
;         ISSUE_UP();
;         const LAS unsigned char* cb = sb + slot_c * STG_BYTES + lane * 16;
; #pragma unroll
;         for (int u = 0; u < 2; ++u) {
;             const int kb = 2 * sbk + u; const bool cA = kb <= qbA && kb + 64 >= qbA, cB = kb <= qbB && kb + 64 >= qbB;
;             if (cA || cB) {
;                 bf16x8 kf[4], vf[2][2];
;                 LOADK(kf, cb + u * 8192); LOADV(vf, cb + u * 8192);
;                 if (cA) { f32x16 tA; LOADT(tA, tb - (qbA - kb) * 128); SCHED_FENCE(); sub_A(kf, vf, qfA, tA, oA0, oA1, lA); }
;                 if (cB) { f32x16 tB; LOADT(tB, tb - (qbB - kb) * 128); SCHED_FENCE(); sub_A(kf, vf, qfB, tB, oB0, oB1, lB); }
;             }
;         }
;         WAITBAR2();
;         slot_c = slot_c == NSTG - 1 ? 0 : slot_c + 1;
;     }
	s_add_i32 s0, s54, 1
	s_add_i32 s1, s35, 1
	s_cmp_lg_u32 s35, 2
	s_cselect_b32 s35, s1, 0
	s_add_i32 s1, s53, 1
	s_cmp_lg_u32 s53, 2
	s_cselect_b32 s53, s1, 0
	s_add_i32 s1, s54, -2
	s_add_i32 s52, s52, 2
	s_cmp_lt_i32 s1, s27
	v_add_u32_e32 v154, 0x100, v154
	s_cbranch_scc0 .Lattn_a_dense_exit
	s_mov_b32 s54, s0
	s_min_i32 s0, s54, s27
	s_ashr_i32 s1, s0, 31
	s_lshl_b32 s55, s35, 14
	s_lshl_b64 s[18:19], s[0:1], 18
	v_lshl_add_u64 v[14:15], v[150:151], 0, s[18:19]
	s_add_i32 s18, s31, s55
	s_lshl_b32 s0, s0, 6
	v_lshl_add_u64 v[14:15], v[14:15], 0, s[12:13]
	s_add_i32 m0, s18, 0x8900
	s_ashr_i32 s1, s0, 31
	global_load_lds_dwordx4 v[14:15], off
	v_lshl_add_u64 v[14:15], s[0:1], 1, v[152:153]
	s_add_i32 m0, s18, 0x9900
	s_lshl_b32 s55, s53, 14
	global_load_lds_dwordx4 v[14:15], off
	v_add_u32_e32 v0, s55, v179
	s_cmp_lt_i32 s52, s30
	s_cbranch_scc0 .Lattn_a_dense_to_slow
	ds_read_b128 v[144:147], v0 offset:35072
	ds_read_b128 v[140:143], v0 offset:36096
	ds_read_b128 v[136:139], v0 offset:37120
	ds_read_b128 v[132:135], v0 offset:38144
	ds_read_b128 v[80:83], v154 offset:1024
	ds_read_b128 v[84:87], v154 offset:1040
	ds_read_b128 v[88:91], v154 offset:1088
	ds_read_b128 v[92:95], v154 offset:1104
	v_mfma_f32_32x32x16_bf16 v[64:79], v[128:131], v[194:197], v[64:79]
	v_exp_f32_e32 v206, v206
	v_exp_f32_e32 v207, v207
	v_exp_f32_e32 v208, v208
	v_exp_f32_e32 v209, v209
	v_add_f32_e32 v155, v206, v155
	v_add_f32_e32 v155, v207, v155
	v_add_f32_e32 v155, v208, v155
	v_add_f32_e32 v155, v209, v155
	v_cvt_pk_bf16_f32 v158, v206, v207
	v_cvt_pk_bf16_f32 v159, v208, v209
	v_mfma_f32_32x32x16_bf16 v[48:63], v[10:13], v[194:197], v[48:63]
	v_exp_f32_e32 v210, v210
	v_exp_f32_e32 v211, v211
	v_exp_f32_e32 v212, v212
	v_exp_f32_e32 v213, v213
	v_add_f32_e32 v155, v210, v155
	v_add_f32_e32 v155, v211, v155
	v_add_f32_e32 v155, v212, v155
	v_add_f32_e32 v155, v213, v155
	v_cvt_pk_bf16_f32 v160, v210, v211
	v_cvt_pk_bf16_f32 v161, v212, v213
	v_mfma_f32_32x32x16_bf16 v[64:79], v[6:9], v[198:201], v[64:79]
	v_exp_f32_e32 v214, v214
	v_exp_f32_e32 v215, v215
	v_exp_f32_e32 v216, v216
	v_exp_f32_e32 v217, v217
	v_add_f32_e32 v155, v214, v155
	v_add_f32_e32 v155, v215, v155
	v_add_f32_e32 v155, v216, v155
	v_add_f32_e32 v155, v217, v155
	v_cvt_pk_bf16_f32 v162, v214, v215
	v_cvt_pk_bf16_f32 v163, v216, v217
	v_mfma_f32_32x32x16_bf16 v[48:63], v[2:5], v[198:201], v[48:63]
	v_exp_f32_e32 v218, v218
	v_exp_f32_e32 v219, v219
	v_exp_f32_e32 v220, v220
	v_exp_f32_e32 v221, v221
	v_add_f32_e32 v155, v218, v155
	v_add_f32_e32 v155, v219, v155
	v_add_f32_e32 v155, v220, v155
	v_add_f32_e32 v155, v221, v155
	v_cvt_pk_bf16_f32 v164, v218, v219
	v_cvt_pk_bf16_f32 v165, v220, v221
	ds_read_b128 v[206:209], v154 offset:0
	ds_read_b128 v[210:213], v154 offset:16
	ds_read_b128 v[214:217], v154 offset:64
	ds_read_b128 v[218:221], v154 offset:80
	v_mfma_f32_32x32x16_bf16 v[32:47], v[128:131], v[158:161], v[32:47]
	v_mfma_f32_32x32x16_bf16 v[16:31], v[10:13], v[158:161], v[16:31]
	v_mfma_f32_32x32x16_bf16 v[32:47], v[6:9], v[162:165], v[32:47]
	v_mfma_f32_32x32x16_bf16 v[16:31], v[2:5], v[162:165], v[16:31]
	s_branch .Lattn_a_dense_top
.Lattn_a_dense_to_slow:
	v_mfma_f32_32x32x16_bf16 v[64:79], v[128:131], v[194:197], v[64:79]
	v_exp_f32_e32 v206, v206
	v_exp_f32_e32 v207, v207
	v_exp_f32_e32 v208, v208
	v_exp_f32_e32 v209, v209
	v_add_f32_e32 v155, v206, v155
	v_add_f32_e32 v155, v207, v155
	v_add_f32_e32 v155, v208, v155
	v_add_f32_e32 v155, v209, v155
	v_cvt_pk_bf16_f32 v158, v206, v207
	v_cvt_pk_bf16_f32 v159, v208, v209
	v_mfma_f32_32x32x16_bf16 v[48:63], v[10:13], v[194:197], v[48:63]
	v_exp_f32_e32 v210, v210
	v_exp_f32_e32 v211, v211
	v_exp_f32_e32 v212, v212
	v_exp_f32_e32 v213, v213
	v_add_f32_e32 v155, v210, v155
	v_add_f32_e32 v155, v211, v155
	v_add_f32_e32 v155, v212, v155
	v_add_f32_e32 v155, v213, v155
	v_cvt_pk_bf16_f32 v160, v210, v211
	v_cvt_pk_bf16_f32 v161, v212, v213
	v_mfma_f32_32x32x16_bf16 v[64:79], v[6:9], v[198:201], v[64:79]
	v_exp_f32_e32 v214, v214
	v_exp_f32_e32 v215, v215
	v_exp_f32_e32 v216, v216
	v_exp_f32_e32 v217, v217
	v_add_f32_e32 v155, v214, v155
	v_add_f32_e32 v155, v215, v155
	v_add_f32_e32 v155, v216, v155
	v_add_f32_e32 v155, v217, v155
	v_cvt_pk_bf16_f32 v162, v214, v215
	v_cvt_pk_bf16_f32 v163, v216, v217
	v_mfma_f32_32x32x16_bf16 v[48:63], v[2:5], v[198:201], v[48:63]
	v_exp_f32_e32 v218, v218
	v_exp_f32_e32 v219, v219
	v_exp_f32_e32 v220, v220
	v_exp_f32_e32 v221, v221
	v_add_f32_e32 v155, v218, v155
	v_add_f32_e32 v155, v219, v155
	v_add_f32_e32 v155, v220, v155
	v_add_f32_e32 v155, v221, v155
	v_cvt_pk_bf16_f32 v164, v218, v219
	v_cvt_pk_bf16_f32 v165, v220, v221
	v_mfma_f32_32x32x16_bf16 v[32:47], v[128:131], v[158:161], v[32:47]
	v_mfma_f32_32x32x16_bf16 v[16:31], v[10:13], v[158:161], v[16:31]
	v_mfma_f32_32x32x16_bf16 v[32:47], v[6:9], v[162:165], v[32:47]
	v_mfma_f32_32x32x16_bf16 v[16:31], v[2:5], v[162:165], v[16:31]
	s_branch .Lattn_a_slow
